# phase D preamble: score-bound reduction loop (34 iterations of load->vmcnt(0)->max) replaced by 34 loads issued together, one wait, v_max3 reduction
# speedup vs baseline: 1.0141x; 1.0040x over previous
.LBB0_707:
	v_lshlrev_b32_e32 v7, 3, v4
	global_load_dwordx2 v[8:9], v7, s[2:3]
	global_load_dwordx2 v[10:11], v7, s[2:3] offset:2048
	v_add_u32_e32 v7, 0x1000, v7
	global_load_dwordx2 v[12:13], v7, s[2:3]
	global_load_dwordx2 v[14:15], v7, s[2:3] offset:2048
	v_add_u32_e32 v7, 0x1000, v7
	global_load_dwordx2 v[16:17], v7, s[2:3]
	global_load_dwordx2 v[18:19], v7, s[2:3] offset:2048
	v_add_u32_e32 v7, 0x1000, v7
	global_load_dwordx2 v[20:21], v7, s[2:3]
	global_load_dwordx2 v[22:23], v7, s[2:3] offset:2048
	v_add_u32_e32 v7, 0x1000, v7
	global_load_dwordx2 v[24:25], v7, s[2:3]
	global_load_dwordx2 v[26:27], v7, s[2:3] offset:2048
	v_add_u32_e32 v7, 0x1000, v7
	global_load_dwordx2 v[28:29], v7, s[2:3]
	global_load_dwordx2 v[30:31], v7, s[2:3] offset:2048
	v_add_u32_e32 v7, 0x1000, v7
	global_load_dwordx2 v[32:33], v7, s[2:3]
	global_load_dwordx2 v[34:35], v7, s[2:3] offset:2048
	v_add_u32_e32 v7, 0x1000, v7
	global_load_dwordx2 v[36:37], v7, s[2:3]
	global_load_dwordx2 v[38:39], v7, s[2:3] offset:2048
	v_add_u32_e32 v7, 0x1000, v7
	global_load_dwordx2 v[40:41], v7, s[2:3]
	global_load_dwordx2 v[42:43], v7, s[2:3] offset:2048
	v_add_u32_e32 v7, 0x1000, v7
	global_load_dwordx2 v[44:45], v7, s[2:3]
	global_load_dwordx2 v[46:47], v7, s[2:3] offset:2048
	v_add_u32_e32 v7, 0x1000, v7
	global_load_dwordx2 v[48:49], v7, s[2:3]
	global_load_dwordx2 v[50:51], v7, s[2:3] offset:2048
	v_add_u32_e32 v7, 0x1000, v7
	global_load_dwordx2 v[52:53], v7, s[2:3]
	global_load_dwordx2 v[54:55], v7, s[2:3] offset:2048
	v_add_u32_e32 v7, 0x1000, v7
	global_load_dwordx2 v[56:57], v7, s[2:3]
	global_load_dwordx2 v[58:59], v7, s[2:3] offset:2048
	v_add_u32_e32 v7, 0x1000, v7
	global_load_dwordx2 v[60:61], v7, s[2:3]
	global_load_dwordx2 v[62:63], v7, s[2:3] offset:2048
	v_add_u32_e32 v7, 0x1000, v7
	global_load_dwordx2 v[64:65], v7, s[2:3]
	global_load_dwordx2 v[66:67], v7, s[2:3] offset:2048
	v_add_u32_e32 v7, 0x1000, v7
	global_load_dwordx2 v[68:69], v7, s[2:3]
	global_load_dwordx2 v[70:71], v7, s[2:3] offset:2048
	v_add_u32_e32 v7, 0x1000, v7
	global_load_dwordx2 v[72:73], v7, s[2:3]
	global_load_dwordx2 v[74:75], v7, s[2:3] offset:2048
	s_waitcnt vmcnt(0)
	v_max3_f32 v6, v6, v8, v10
	v_max3_f32 v5, v5, v9, v11
	v_max3_f32 v6, v6, v12, v14
	v_max3_f32 v5, v5, v13, v15
	v_max3_f32 v6, v6, v16, v18
	v_max3_f32 v5, v5, v17, v19
	v_max3_f32 v6, v6, v20, v22
	v_max3_f32 v5, v5, v21, v23
	v_max3_f32 v6, v6, v24, v26
	v_max3_f32 v5, v5, v25, v27
	v_max3_f32 v6, v6, v28, v30
	v_max3_f32 v5, v5, v29, v31
	v_max3_f32 v6, v6, v32, v34
	v_max3_f32 v5, v5, v33, v35
	v_max3_f32 v6, v6, v36, v38
	v_max3_f32 v5, v5, v37, v39
	v_max3_f32 v6, v6, v40, v42
	v_max3_f32 v5, v5, v41, v43
	v_max3_f32 v6, v6, v44, v46
	v_max3_f32 v5, v5, v45, v47
	v_max3_f32 v6, v6, v48, v50
	v_max3_f32 v5, v5, v49, v51
	v_max3_f32 v6, v6, v52, v54
	v_max3_f32 v5, v5, v53, v55
	v_max3_f32 v6, v6, v56, v58
	v_max3_f32 v5, v5, v57, v59
	v_max3_f32 v6, v6, v60, v62
	v_max3_f32 v5, v5, v61, v63
	v_max3_f32 v6, v6, v64, v66
	v_max3_f32 v5, v5, v65, v67
	v_max3_f32 v6, v6, v68, v70
	v_max3_f32 v5, v5, v69, v71
	v_max3_f32 v6, v6, v72, v74
	v_max3_f32 v5, v5, v73, v75
